# plus out-projection epilogue: residual loads of row blocks 1-2 issued with the initial batch
# baseline (speedup 1.0000x reference)
.LBB0_496:
	s_ashr_i32 s19, s38, 4
	s_mul_hi_i32 s25, s19, 0x6000
	s_mulk_i32 s19, 0x6000
	v_lshl_add_u32 v156, s38, 8, v1
	v_lshl_or_b32 v154, s8, 8, v169
	s_add_u32 s40, s68, s19
	v_ashrrev_i32_e32 v157, 31, v156
	s_addc_u32 s41, s69, s25
	v_ashrrev_i32_e32 v155, 31, v154
	v_lshlrev_b64 v[74:75], 10, v[156:157]
	v_lshl_add_u64 v[200:201], v[74:75], 0, v[154:155]
	s_add_u32 s38, s70, s19
	v_lshlrev_b64 v[166:167], 2, v[154:155]
	v_lshl_add_u64 v[206:207], v[200:201], 2, s[36:37]
	s_addc_u32 s39, s71, s25
	v_lshl_add_u64 v[198:199], s[40:41], 0, v[166:167]
	global_load_dwordx4 v[158:161], v[206:207], off
	global_load_dwordx4 v[78:81], v[198:199], off
	global_load_dwordx4 v[74:77], v[198:199], off offset:16
	global_load_dwordx4 v[162:165], v[206:207], off offset:16
	v_lshl_add_u64 v[202:203], s[38:39], 0, v[166:167]
	global_load_dwordx4 v[174:177], v[202:203], off
	global_load_dwordx4 v[178:181], v[202:203], off offset:16
	v_lshl_add_u64 v[166:167], s[50:51], 0, v[166:167]
	global_load_dwordx4 v[182:185], v[166:167], off
	global_load_dwordx4 v[186:189], v[166:167], off offset:16
	v_pk_add_f32 v[208:209], v[88:89], 0 op_sel_hi:[1,0]
	v_pk_add_f32 v[210:211], v[86:87], 0 op_sel_hi:[1,0]
	v_pk_add_f32 v[212:213], v[84:85], 0 op_sel_hi:[1,0]
	v_pk_add_f32 v[214:215], v[82:83], 0 op_sel_hi:[1,0]
	global_load_dwordx4 v[190:193], v[166:167], off offset:528
	global_load_dwordx4 v[194:197], v[166:167], off offset:512
	v_lshlrev_b64 v[166:167], 1, v[200:201]
	v_lshl_add_u64 v[216:217], s[20:21], 0, v[166:167]
	v_lshl_add_u64 v[218:219], s[22:23], 0, v[166:167]
	global_load_dwordx4 v[82:85], v[198:199], off offset:528
	global_load_dwordx4 v[86:89], v[198:199], off offset:512
	s_nop 0
	global_load_dwordx4 v[198:201], v[202:203], off offset:528
	s_nop 0
	global_load_dwordx4 v[202:205], v[202:203], off offset:512
	v_add_co_u32_e32 v252, vcc, 0x10000, v206
	s_nop 1
	v_addc_co_u32_e32 v253, vcc, 0, v207, vcc
	global_load_dwordx4 v[220:223], v[252:253], off
	global_load_dwordx4 v[224:227], v[252:253], off offset:16
	global_load_dwordx4 v[228:231], v[252:253], off offset:512
	global_load_dwordx4 v[232:235], v[252:253], off offset:528
	v_add_co_u32_e32 v252, vcc, 0x20000, v206
	s_nop 1
	v_addc_co_u32_e32 v253, vcc, 0, v207, vcc
	global_load_dwordx4 v[236:239], v[252:253], off
	global_load_dwordx4 v[240:243], v[252:253], off offset:16
	global_load_dwordx4 v[244:247], v[252:253], off offset:512
	global_load_dwordx4 v[248:251], v[252:253], off offset:528
	s_lshl_b32 s38, s8, 2
	s_ashr_i32 s39, s38, 31
	s_waitcnt vmcnt(0)
	v_pk_fma_f32 v[166:167], v[208:209], v[80:81], v[160:161]
	v_pk_fma_f32 v[208:209], v[210:211], v[78:79], v[158:159]
	v_pk_fma_f32 v[210:211], v[212:213], v[76:77], v[164:165]
	v_pk_fma_f32 v[212:213], v[214:215], v[74:75], v[162:163]
	v_cvt_pk_bf16_f32 v158, v208, v209
	v_cvt_pk_bf16_f32 v159, v166, v167
	v_cvt_pk_bf16_f32 v160, v212, v213
	v_cvt_pk_bf16_f32 v161, v210, v211
	v_pk_add_f32 v[162:163], v[176:177], 1.0 op_sel_hi:[1,0]
	v_pk_add_f32 v[164:165], v[174:175], 1.0 op_sel_hi:[1,0]
	v_pk_add_f32 v[174:175], v[180:181], 1.0 op_sel_hi:[1,0]
	v_pk_add_f32 v[176:177], v[178:179], 1.0 op_sel_hi:[1,0]
	global_store_dwordx4 v[216:217], v[158:161], off
	v_pk_mul_f32 v[164:165], v[182:183], v[164:165]
	v_pk_add_f32 v[198:199], v[198:199], 1.0 op_sel_hi:[1,0]
	v_pk_mul_f32 v[160:161], v[184:185], v[162:163]
	v_pk_mul_f32 v[158:159], v[188:189], v[174:175]
	v_pk_mul_f32 v[162:163], v[186:187], v[176:177]
	v_pk_mul_f32 v[176:177], v[160:161], v[166:167]
	v_pk_mul_f32 v[174:175], v[164:165], v[208:209]
	v_pk_mul_f32 v[178:179], v[158:159], v[210:211]
	v_pk_mul_f32 v[180:181], v[162:163], v[212:213]
	v_cvt_pk_bf16_f32 v174, v174, v175
	v_cvt_pk_bf16_f32 v175, v176, v177
	v_cvt_pk_bf16_f32 v176, v180, v181
	v_cvt_pk_bf16_f32 v177, v178, v179
	global_store_dwordx4 v[218:219], v[174:177], off
	global_load_dwordx4 v[176:179], v[206:207], off offset:512
	s_nop 0
	global_load_dwordx4 v[180:183], v[206:207], off offset:528
	v_pk_add_f32 v[206:207], v[130:131], 0 op_sel_hi:[1,0]
	v_and_b32_e32 v131, 64, v173
	v_xor_b32_e32 v130, 16, v173
	v_add_u32_e32 v131, 64, v131
	v_pk_add_f32 v[188:189], v[132:133], 0 op_sel_hi:[1,0]
	v_xor_b32_e32 v132, 32, v173
	v_cmp_lt_i32_e32 vcc, v130, v131
	v_mul_f32_e32 v209, v209, v209
	v_mul_f32_e32 v167, v167, v167
	v_mul_f32_e32 v213, v213, v213
	v_mul_f32_e32 v211, v211, v211
	v_cndmask_b32_e32 v130, v173, v130, vcc
	v_cmp_lt_i32_e32 vcc, v132, v131
	v_fmac_f32_e32 v209, v208, v208
	v_fmac_f32_e32 v167, v166, v166
	v_fmac_f32_e32 v213, v212, v212
	v_fmac_f32_e32 v211, v210, v210
	v_pk_add_f32 v[184:185], v[136:137], 0 op_sel_hi:[1,0]
	v_pk_add_f32 v[186:187], v[134:135], 0 op_sel_hi:[1,0]
	v_cndmask_b32_e32 v175, v173, v132, vcc
	v_pk_add_f32 v[132:133], v[202:203], 1.0 op_sel_hi:[1,0]
	v_add_f32_e32 v166, v209, v167
	v_add_f32_e32 v167, v213, v211
	v_lshlrev_b32_e32 v174, 2, v130
	v_pk_add_f32 v[130:131], v[204:205], 1.0 op_sel_hi:[1,0]
	v_pk_add_f32 v[200:201], v[200:201], 1.0 op_sel_hi:[1,0]
	v_pk_mul_f32 v[134:135], v[194:195], v[132:133]
	v_pk_mul_f32 v[132:133], v[190:191], v[198:199]
	v_add_f32_e32 v190, v166, v167
	v_pk_mul_f32 v[136:137], v[196:197], v[130:131]
	v_pk_mul_f32 v[130:131], v[192:193], v[200:201]
	v_lshlrev_b32_e32 v175, 2, v175
	s_waitcnt vmcnt(1)
	v_pk_fma_f32 v[166:167], v[184:185], v[88:89], v[178:179]
	v_pk_fma_f32 v[184:185], v[186:187], v[86:87], v[176:177]
	s_waitcnt vmcnt(0)
	v_pk_fma_f32 v[182:183], v[188:189], v[84:85], v[182:183]
	v_pk_fma_f32 v[180:181], v[206:207], v[82:83], v[180:181]
	v_mul_f32_e32 v191, v185, v185
	v_mul_f32_e32 v192, v167, v167
	v_mul_f32_e32 v193, v181, v181
	v_mul_f32_e32 v194, v183, v183
	v_fmac_f32_e32 v191, v184, v184
	v_fmac_f32_e32 v192, v166, v166
	v_fmac_f32_e32 v193, v180, v180
	v_fmac_f32_e32 v194, v182, v182
	v_cvt_pk_bf16_f32 v177, v166, v167
	v_pk_mul_f32 v[186:187], v[136:137], v[166:167]
	v_add_f32_e32 v166, v191, v192
	v_add_f32_e32 v167, v193, v194
	v_add_f32_e32 v166, v166, v167
	v_add_f32_e32 v166, v190, v166
	ds_bpermute_b32 v167, v174, v166
	v_cvt_pk_bf16_f32 v176, v184, v185
	v_cvt_pk_bf16_f32 v178, v180, v181
	v_cvt_pk_bf16_f32 v179, v182, v183
	v_pk_mul_f32 v[188:189], v[134:135], v[184:185]
	s_waitcnt lgkmcnt(0)
	v_add_f32_e32 v166, v166, v167
	ds_bpermute_b32 v167, v175, v166
	v_pk_mul_f32 v[182:183], v[130:131], v[182:183]
	v_pk_mul_f32 v[180:181], v[132:133], v[180:181]
	global_store_dwordx4 v[216:217], v[176:179], off offset:256
	s_nop 1
	v_cvt_pk_bf16_f32 v176, v188, v189
	v_cvt_pk_bf16_f32 v177, v186, v187
	v_cvt_pk_bf16_f32 v178, v180, v181
	v_cvt_pk_bf16_f32 v179, v182, v183
	global_store_dwordx4 v[218:219], v[176:179], off offset:256
	s_and_saveexec_b64 s[40:41], s[0:1]
	s_cbranch_execz .LBB0_498
	v_lshlrev_b64 v[176:177], 6, v[156:157]
	v_lshl_add_u64 v[176:177], s[12:13], 0, v[176:177]
	v_lshl_add_u64 v[176:177], s[38:39], 2, v[176:177]
	s_lshl_b32 s8, s72, 2
	v_lshl_add_u64 v[176:177], v[176:177], 0, s[8:9]
	s_waitcnt lgkmcnt(0)
	v_add_f32_e32 v157, v166, v167
	global_store_dword v[176:177], v157, off
.LBB0_498:
	s_or_b64 exec, exec, s[40:41]
	v_or_b32_e32 v166, 16, v156
	s_waitcnt lgkmcnt(0)
	v_ashrrev_i32_e32 v167, 31, v166
	v_lshlrev_b64 v[176:177], 10, v[166:167]
	v_lshl_add_u64 v[184:185], v[176:177], 0, v[154:155]
	v_lshl_add_u64 v[186:187], v[184:185], 2, s[36:37]
	s_nop 1
	v_pk_mov_b32 v[176:177], v[220:221], v[220:221] op_sel:[0,1]
	v_pk_mov_b32 v[178:179], v[222:223], v[222:223] op_sel:[0,1]
	s_nop 1
	v_pk_mov_b32 v[180:181], v[224:225], v[224:225] op_sel:[0,1]
	v_pk_mov_b32 v[182:183], v[226:227], v[226:227] op_sel:[0,1]
	v_pk_add_f32 v[128:129], v[128:129], 0 op_sel_hi:[1,0]
	v_pk_add_f32 v[126:127], v[126:127], 0 op_sel_hi:[1,0]
	v_pk_add_f32 v[124:125], v[124:125], 0 op_sel_hi:[1,0]
	v_pk_add_f32 v[122:123], v[122:123], 0 op_sel_hi:[1,0]
	v_lshlrev_b64 v[184:185], 1, v[184:185]
	v_lshl_add_u64 v[188:189], s[20:21], 0, v[184:185]
	v_lshl_add_u64 v[184:185], s[22:23], 0, v[184:185]
	v_pk_add_f32 v[120:121], v[120:121], 0 op_sel_hi:[1,0]
	v_pk_add_f32 v[118:119], v[118:119], 0 op_sel_hi:[1,0]
	v_pk_add_f32 v[116:117], v[116:117], 0 op_sel_hi:[1,0]
	v_pk_add_f32 v[114:115], v[114:115], 0 op_sel_hi:[1,0]
	v_pk_fma_f32 v[178:179], v[128:129], v[80:81], v[178:179]
	v_pk_fma_f32 v[176:177], v[126:127], v[78:79], v[176:177]
	v_pk_fma_f32 v[182:183], v[124:125], v[76:77], v[182:183]
	v_pk_fma_f32 v[180:181], v[122:123], v[74:75], v[180:181]
	v_cvt_pk_bf16_f32 v122, v176, v177
	v_cvt_pk_bf16_f32 v123, v178, v179
	v_cvt_pk_bf16_f32 v124, v180, v181
	v_cvt_pk_bf16_f32 v125, v182, v183
	v_pk_mul_f32 v[126:127], v[160:161], v[178:179]
	v_pk_mul_f32 v[128:129], v[164:165], v[176:177]
	v_pk_mul_f32 v[190:191], v[158:159], v[182:183]
	v_pk_mul_f32 v[192:193], v[162:163], v[180:181]
	global_store_dwordx4 v[188:189], v[122:125], off
	v_mul_f32_e32 v157, v177, v177
	v_mul_f32_e32 v177, v179, v179
	v_cvt_pk_bf16_f32 v122, v128, v129
	v_cvt_pk_bf16_f32 v123, v126, v127
	v_cvt_pk_bf16_f32 v124, v192, v193
	v_cvt_pk_bf16_f32 v125, v190, v191
	global_store_dwordx4 v[184:185], v[122:125], off
	s_nop 1
	v_pk_mov_b32 v[122:123], v[228:229], v[228:229] op_sel:[0,1]
	v_pk_mov_b32 v[124:125], v[230:231], v[230:231] op_sel:[0,1]
	s_nop 0
	s_nop 1
	v_pk_mov_b32 v[126:127], v[232:233], v[232:233] op_sel:[0,1]
	v_pk_mov_b32 v[128:129], v[234:235], v[234:235] op_sel:[0,1]
	v_mul_f32_e32 v179, v181, v181
	v_mul_f32_e32 v181, v183, v183
	v_fmac_f32_e32 v157, v176, v176
	v_fmac_f32_e32 v177, v178, v178
	v_fmac_f32_e32 v179, v180, v180
	v_fmac_f32_e32 v181, v182, v182
	v_add_f32_e32 v157, v157, v177
	v_add_f32_e32 v176, v179, v181
	v_add_f32_e32 v157, v157, v176
	v_pk_fma_f32 v[120:121], v[120:121], v[88:89], v[124:125]
	v_pk_fma_f32 v[118:119], v[118:119], v[86:87], v[122:123]
	v_pk_fma_f32 v[122:123], v[116:117], v[84:85], v[128:129]
	v_pk_fma_f32 v[124:125], v[114:115], v[82:83], v[126:127]
	v_mul_f32_e32 v126, v119, v119
	v_mul_f32_e32 v127, v121, v121
	v_mul_f32_e32 v128, v125, v125
	v_mul_f32_e32 v129, v123, v123
	v_cvt_pk_bf16_f32 v114, v118, v119
	v_cvt_pk_bf16_f32 v115, v120, v121
	v_cvt_pk_bf16_f32 v116, v124, v125
	v_cvt_pk_bf16_f32 v117, v122, v123
	v_fmac_f32_e32 v126, v118, v118
	v_fmac_f32_e32 v127, v120, v120
	v_fmac_f32_e32 v128, v124, v124
	v_fmac_f32_e32 v129, v122, v122
	global_store_dwordx4 v[188:189], v[114:117], off offset:256
	v_pk_mul_f32 v[120:121], v[136:137], v[120:121]
	v_pk_mul_f32 v[122:123], v[130:131], v[122:123]
	v_add_f32_e32 v114, v126, v127
	v_add_f32_e32 v115, v128, v129
	v_add_f32_e32 v114, v114, v115
	v_add_f32_e32 v117, v157, v114
	ds_bpermute_b32 v126, v174, v117
	v_pk_mul_f32 v[114:115], v[134:135], v[118:119]
	v_pk_mul_f32 v[118:119], v[132:133], v[124:125]
	v_cvt_pk_bf16_f32 v116, v114, v115
	v_cvt_pk_bf16_f32 v118, v118, v119
	s_waitcnt lgkmcnt(0)
	v_add_f32_e32 v114, v117, v126
	ds_bpermute_b32 v115, v175, v114
	v_cvt_pk_bf16_f32 v117, v120, v121
	v_cvt_pk_bf16_f32 v119, v122, v123
	global_store_dwordx4 v[184:185], v[116:119], off offset:256
	s_and_saveexec_b64 s[40:41], s[0:1]
	s_cbranch_execz .LBB0_500
	v_lshlrev_b64 v[116:117], 6, v[166:167]
	v_lshl_add_u64 v[116:117], s[12:13], 0, v[116:117]
	v_lshl_add_u64 v[116:117], s[38:39], 2, v[116:117]
	s_lshl_b32 s8, s72, 2
	v_lshl_add_u64 v[116:117], v[116:117], 0, s[8:9]
	s_waitcnt lgkmcnt(0)
	v_add_f32_e32 v114, v114, v115
	global_store_dword v[116:117], v114, off
.LBB0_500:
	s_or_b64 exec, exec, s[40:41]
	v_or_b32_e32 v114, 32, v156
	s_waitcnt lgkmcnt(0)
	v_ashrrev_i32_e32 v115, 31, v114
	v_lshlrev_b64 v[116:117], 10, v[114:115]
	v_lshl_add_u64 v[124:125], v[116:117], 0, v[154:155]
	v_lshl_add_u64 v[126:127], v[124:125], 2, s[36:37]
	s_nop 1
	v_pk_mov_b32 v[116:117], v[236:237], v[236:237] op_sel:[0,1]
	v_pk_mov_b32 v[118:119], v[238:239], v[238:239] op_sel:[0,1]
	s_nop 1
	v_pk_mov_b32 v[120:121], v[240:241], v[240:241] op_sel:[0,1]
	v_pk_mov_b32 v[122:123], v[242:243], v[242:243] op_sel:[0,1]
	v_pk_add_f32 v[112:113], v[112:113], 0 op_sel_hi:[1,0]
	v_pk_add_f32 v[110:111], v[110:111], 0 op_sel_hi:[1,0]
	v_pk_add_f32 v[108:109], v[108:109], 0 op_sel_hi:[1,0]
	v_pk_add_f32 v[106:107], v[106:107], 0 op_sel_hi:[1,0]
	v_lshlrev_b64 v[124:125], 1, v[124:125]
	v_lshl_add_u64 v[128:129], s[20:21], 0, v[124:125]
	v_lshl_add_u64 v[124:125], s[22:23], 0, v[124:125]
	v_pk_add_f32 v[104:105], v[104:105], 0 op_sel_hi:[1,0]
	v_pk_add_f32 v[102:103], v[102:103], 0 op_sel_hi:[1,0]
	v_pk_add_f32 v[100:101], v[100:101], 0 op_sel_hi:[1,0]
	v_pk_add_f32 v[98:99], v[98:99], 0 op_sel_hi:[1,0]
	v_pk_fma_f32 v[118:119], v[112:113], v[80:81], v[118:119]
	v_pk_fma_f32 v[116:117], v[110:111], v[78:79], v[116:117]
	v_pk_fma_f32 v[122:123], v[108:109], v[76:77], v[122:123]
	v_pk_fma_f32 v[120:121], v[106:107], v[74:75], v[120:121]
	v_cvt_pk_bf16_f32 v106, v116, v117
	v_cvt_pk_bf16_f32 v107, v118, v119
	v_cvt_pk_bf16_f32 v108, v120, v121
	v_cvt_pk_bf16_f32 v109, v122, v123
	v_pk_mul_f32 v[110:111], v[160:161], v[118:119]
	v_pk_mul_f32 v[112:113], v[164:165], v[116:117]
	v_pk_mul_f32 v[166:167], v[158:159], v[122:123]
	v_pk_mul_f32 v[176:177], v[162:163], v[120:121]
	global_store_dwordx4 v[128:129], v[106:109], off
	v_mul_f32_e32 v117, v117, v117
	v_mul_f32_e32 v119, v119, v119
	v_cvt_pk_bf16_f32 v106, v112, v113
	v_cvt_pk_bf16_f32 v107, v110, v111
	v_cvt_pk_bf16_f32 v108, v176, v177
	v_cvt_pk_bf16_f32 v109, v166, v167
	global_store_dwordx4 v[124:125], v[106:109], off
	s_nop 1
	v_pk_mov_b32 v[106:107], v[244:245], v[244:245] op_sel:[0,1]
	v_pk_mov_b32 v[108:109], v[246:247], v[246:247] op_sel:[0,1]
	s_nop 0
	s_nop 1
	v_pk_mov_b32 v[110:111], v[248:249], v[248:249] op_sel:[0,1]
	v_pk_mov_b32 v[112:113], v[250:251], v[250:251] op_sel:[0,1]
	v_mul_f32_e32 v121, v121, v121
	v_mul_f32_e32 v123, v123, v123
	v_fmac_f32_e32 v117, v116, v116
	v_fmac_f32_e32 v119, v118, v118
	v_fmac_f32_e32 v121, v120, v120
	v_fmac_f32_e32 v123, v122, v122
	v_add_f32_e32 v116, v117, v119
	v_add_f32_e32 v117, v121, v123
	v_add_f32_e32 v116, v116, v117
	v_pk_fma_f32 v[104:105], v[104:105], v[88:89], v[108:109]
	v_pk_fma_f32 v[102:103], v[102:103], v[86:87], v[106:107]
	v_pk_fma_f32 v[106:107], v[100:101], v[84:85], v[112:113]
	v_pk_fma_f32 v[108:109], v[98:99], v[82:83], v[110:111]
	v_mul_f32_e32 v110, v103, v103
	v_mul_f32_e32 v111, v105, v105
	v_mul_f32_e32 v112, v109, v109
	v_mul_f32_e32 v113, v107, v107
	v_cvt_pk_bf16_f32 v98, v102, v103
	v_cvt_pk_bf16_f32 v99, v104, v105
	v_cvt_pk_bf16_f32 v100, v108, v109
	v_cvt_pk_bf16_f32 v101, v106, v107
	v_fmac_f32_e32 v110, v102, v102
	v_fmac_f32_e32 v111, v104, v104
	v_fmac_f32_e32 v112, v108, v108
	v_fmac_f32_e32 v113, v106, v106
	global_store_dwordx4 v[128:129], v[98:101], off offset:256
	v_pk_mul_f32 v[104:105], v[136:137], v[104:105]
	v_pk_mul_f32 v[106:107], v[130:131], v[106:107]
	v_add_f32_e32 v98, v110, v111
	v_add_f32_e32 v99, v112, v113
	v_add_f32_e32 v98, v98, v99
	v_add_f32_e32 v101, v116, v98
	ds_bpermute_b32 v110, v174, v101
	v_pk_mul_f32 v[98:99], v[134:135], v[102:103]
	v_pk_mul_f32 v[102:103], v[132:133], v[108:109]
	v_cvt_pk_bf16_f32 v100, v98, v99
	v_cvt_pk_bf16_f32 v102, v102, v103
	s_waitcnt lgkmcnt(0)
	v_add_f32_e32 v98, v101, v110
	ds_bpermute_b32 v99, v175, v98
	v_cvt_pk_bf16_f32 v101, v104, v105
	v_cvt_pk_bf16_f32 v103, v106, v107
	global_store_dwordx4 v[124:125], v[100:103], off offset:256
	s_and_saveexec_b64 s[40:41], s[0:1]
	s_cbranch_execz .LBB0_502
	v_lshlrev_b64 v[100:101], 6, v[114:115]
	v_lshl_add_u64 v[100:101], s[12:13], 0, v[100:101]
	v_lshl_add_u64 v[100:101], s[38:39], 2, v[100:101]
	s_lshl_b32 s8, s72, 2
	v_lshl_add_u64 v[100:101], v[100:101], 0, s[8:9]
	s_waitcnt lgkmcnt(0)
	v_add_f32_e32 v98, v98, v99
	global_store_dword v[100:101], v98, off
